# GLA combine: all earlier-segment flags polled in parallel by lanes of wave 0 (one round trip instead of one per segment)
# baseline (speedup 1.0000x reference)
; __device__ __forceinline__ void gla_scan(const Params& P, LAS unsigned char* lds, int bh, int seg, int nseg, bool dry) {
;     ...
; #pragma unroll
;     for (int kt = 0; kt < 8; ++kt) { S[kt][0] = (f32x4){0.f, 0.f, 0.f, 0.f}; S[kt][1] = (f32x4){0.f, 0.f, 0.f, 0.f}; }
;     if (seg > 0) {
;         if (tid == 0) {
;             for (int i = 0; i < seg; ++i) { unsigned spins = 0;
;                 while (__hip_atomic_load(FL + (bh * 4 + i) * 16, __ATOMIC_RELAXED, __HIP_MEMORY_SCOPE_AGENT) == 0u && ++spins < (1u << 22)) __builtin_amdgcn_s_sleep(2); }
;             __builtin_amdgcn_fence(__ATOMIC_ACQUIRE, "agent"); asm volatile("s_waitcnt vmcnt(0)" ::: "memory");
;         }
;         __syncthreads();
.LBB0_673:
	v_bfe_u32 v100, v114, 4, 2
	v_mov_b32_e32 v35, 0
	s_cmp_lt_u32 s2, 32
	v_mov_b32_e32 v34, 0
	v_mov_b32_e32 v33, 0
	v_mov_b32_e32 v32, 0
	s_waitcnt vmcnt(2)
	v_mov_b32_e32 v3, 0
	v_mov_b32_e32 v2, 0
	v_mov_b32_e32 v1, 0
	v_mov_b32_e32 v0, 0
	v_mov_b32_e32 v7, 0
	v_mov_b32_e32 v6, 0
	v_mov_b32_e32 v5, 0
	v_mov_b32_e32 v4, 0
	v_mov_b32_e32 v11, 0
	v_mov_b32_e32 v10, 0
	v_mov_b32_e32 v9, 0
	v_mov_b32_e32 v8, 0
	v_mov_b32_e32 v15, 0
	v_mov_b32_e32 v14, 0
	v_mov_b32_e32 v13, 0
	v_mov_b32_e32 v12, 0
	v_mov_b32_e32 v19, 0
	v_mov_b32_e32 v18, 0
	v_mov_b32_e32 v17, 0
	v_mov_b32_e32 v16, 0
	v_mov_b32_e32 v23, 0
	v_mov_b32_e32 v22, 0
	v_mov_b32_e32 v21, 0
	v_mov_b32_e32 v20, 0
	v_mov_b32_e32 v27, 0
	v_mov_b32_e32 v26, 0
	v_mov_b32_e32 v25, 0
	v_mov_b32_e32 v24, 0
	v_mov_b32_e32 v39, 0
	v_mov_b32_e32 v38, 0
	v_mov_b32_e32 v37, 0
	v_mov_b32_e32 v36, 0
	v_mov_b32_e32 v31, 0
	v_mov_b32_e32 v30, 0
	v_mov_b32_e32 v29, 0
	v_mov_b32_e32 v28, 0
	v_mov_b32_e32 v43, 0
	v_mov_b32_e32 v42, 0
	v_mov_b32_e32 v41, 0
	v_mov_b32_e32 v40, 0
	v_mov_b32_e32 v47, 0
	v_mov_b32_e32 v46, 0
	v_mov_b32_e32 v45, 0
	v_mov_b32_e32 v44, 0
	v_mov_b32_e32 v51, 0
	v_mov_b32_e32 v50, 0
	v_mov_b32_e32 v49, 0
	v_mov_b32_e32 v48, 0
	v_mov_b32_e32 v55, 0
	v_mov_b32_e32 v54, 0
	v_mov_b32_e32 v53, 0
	v_mov_b32_e32 v52, 0
	v_mov_b32_e32 v59, 0
	v_mov_b32_e32 v58, 0
	v_mov_b32_e32 v57, 0
	v_mov_b32_e32 v56, 0
	v_mov_b32_e32 v63, 0
	v_mov_b32_e32 v62, 0
	v_mov_b32_e32 v61, 0
	v_mov_b32_e32 v60, 0
	s_cbranch_scc1 .LBB0_692
	v_cmp_gt_u32_e32 vcc, s3, v114
	s_and_saveexec_b64 s[4:5], vcc
	s_cbranch_execz .LBB0_689
	s_lshl_b32 s13, s1, 8
	v_lshlrev_b32_e32 v0, 6, v114
	s_mov_b32 s14, 0x400000
	v_add_u32_e32 v0, s13, v0
.Lcmb_poll:
	global_load_dword v1, v0, s[20:21] sc1
	s_add_i32 s14, s14, -1
	s_waitcnt vmcnt(0)
	v_cmp_eq_u32_e32 vcc, 0, v1
	s_cbranch_vccz .Lcmb_polled
	s_cmp_eq_u32 s14, 0
	s_cbranch_scc1 .Lcmb_polled
	s_sleep 2
	s_branch .Lcmb_poll
